# v13 + M7 branch-merge epilogue regenerated: final/non-final segment specialised (no select), packed muls; same f32 ops
# speedup vs baseline: 1.0082x; 1.0044x over previous
; __device__ __forceinline__ unsigned cvt_pk_bf16(float lo, float hi) { f32x2c v = {lo, hi}; bf16x2c b = __builtin_convertvector(v, bf16x2c); return __builtin_bit_cast(unsigned, b); }
; __device__ __forceinline__ float ub0(unsigned w) { return (float)(w & 0xFFu); }
; __device__ __forceinline__ float ub1(unsigned w) { return (float)((w >> 8) & 0xFFu); }
; __device__ __forceinline__ float ub2(unsigned w) { return (float)((w >> 16) & 0xFFu); }
; __device__ __forceinline__ float ub3(unsigned w) { return (float)(w >> 24); }
;     __device__ __forceinline__ void operator()(f32x4 (&acc)[2][2][4][2], const Unit& u, int wr, int wc, int fr, int fq) const {
;     ...
;                 for (int bj = 0; bj < 2; ++bj) { const u32x2 a = gn[ai][m][bj], d = gd[ai][m][bj];
;                     const float an[8] = {ub0(a.x), ub1(a.x), ub2(a.x), ub3(a.x), ub0(a.y), ub1(a.y), ub2(a.y), ub3(a.y)};
;                     const float dn[8] = {ub0(d.x), ub1(d.x), ub2(d.x), ub3(d.x), ub0(d.y), ub1(d.y), ub2(d.y), ub3(d.y)};
;                     float f[8];
; #pragma unroll
;                     for (int k = 0; k < 8; ++k) { const float rd = __builtin_amdgcn_rcpf(dn[k]); f[k] = an[k] * (fin ? (1.0f / 255.0f) : rd); }
;                     f32x4 v0 = acc[ai][bj][m][0], v1 = acc[ai][bj][m][1];
;                     v0[0] *= f[0]; v0[1] *= f[1]; v0[2] *= f[2]; v0[3] *= f[3]; v1[0] *= f[4]; v1[1] *= f[5]; v1[2] *= f[6]; v1[3] *= f[7];
;                     acc[ai][bj][m][0] = v0; acc[ai][bj][m][1] = v1;
;                     if (fin) { u32x4 w; w.x = cvt_pk_bf16(v0[0], v0[1]); w.y = cvt_pk_bf16(v0[2], v0[3]); w.z = cvt_pk_bf16(v1[0], v1[1]); w.w = cvt_pk_bf16(v1[2], v1[3]);
;                         *(u32x4*)(MO + (size_t)(row0 + ai * HALF + m * 16) * ld + col0 + bj * HALF) = w; } }
.LBB0_2028:
	s_cmp_lg_u64 s[40:41], 0
	s_cbranch_scc1 .Lm7f_0
	v_cvt_f32_ubyte0_e32 v238, v227
	v_cvt_f32_ubyte1_e32 v239, v227
	v_cvt_f32_ubyte2_e32 v240, v227
	v_cvt_f32_ubyte3_e32 v241, v227
	v_cvt_f32_ubyte0_e32 v242, v226
	v_cvt_f32_ubyte1_e32 v243, v226
	v_cvt_f32_ubyte2_e32 v244, v226
	v_cvt_f32_ubyte3_e32 v245, v226
	v_cvt_f32_ubyte0_e32 v246, v225
	v_cvt_f32_ubyte1_e32 v247, v225
	v_cvt_f32_ubyte2_e32 v248, v225
	v_cvt_f32_ubyte3_e32 v249, v225
	v_cvt_f32_ubyte0_e32 v250, v224
	v_cvt_f32_ubyte1_e32 v251, v224
	v_cvt_f32_ubyte2_e32 v252, v224
	v_cvt_f32_ubyte3_e32 v253, v224
	v_rcp_iflag_f32_e32 v246, v246
	v_rcp_iflag_f32_e32 v247, v247
	v_rcp_iflag_f32_e32 v248, v248
	v_rcp_iflag_f32_e32 v249, v249
	v_rcp_iflag_f32_e32 v250, v250
	v_rcp_iflag_f32_e32 v251, v251
	v_rcp_iflag_f32_e32 v252, v252
	v_rcp_iflag_f32_e32 v253, v253
	v_pk_mul_f32 v[238:239], v[238:239], v[246:247]
	v_pk_mul_f32 v[240:241], v[240:241], v[248:249]
	v_pk_mul_f32 v[242:243], v[242:243], v[250:251]
	v_pk_mul_f32 v[244:245], v[244:245], v[252:253]
	v_pk_mul_f32 v[92:93], v[92:93], v[238:239]
	v_pk_mul_f32 v[94:95], v[94:95], v[240:241]
	v_pk_mul_f32 v[96:97], v[96:97], v[242:243]
	v_pk_mul_f32 v[98:99], v[98:99], v[244:245]
	v_cndmask_b32_e64 v224, 0, 1, s[40:41]
	v_cmp_ne_u32_e64 s[42:43], 1, v224
	s_branch .LBB0_2030
.Lm7f_0:
	s_nop 1
	v_cvt_f32_ubyte0_e32 v238, v227
	v_cvt_f32_ubyte1_e32 v239, v227
	v_cvt_f32_ubyte2_e32 v240, v227
	v_cvt_f32_ubyte3_e32 v241, v227
	v_cvt_f32_ubyte0_e32 v242, v226
	v_cvt_f32_ubyte1_e32 v243, v226
	v_cvt_f32_ubyte2_e32 v244, v226
	v_cvt_f32_ubyte3_e32 v245, v226
	v_pk_mul_f32 v[238:239], v[238:239], v[232:233] op_sel:[0,1] op_sel_hi:[1,1]
	v_pk_mul_f32 v[240:241], v[240:241], v[232:233] op_sel:[0,1] op_sel_hi:[1,1]
	v_pk_mul_f32 v[242:243], v[242:243], v[232:233] op_sel:[0,1] op_sel_hi:[1,1]
	v_pk_mul_f32 v[244:245], v[244:245], v[232:233] op_sel:[0,1] op_sel_hi:[1,1]
	v_pk_mul_f32 v[92:93], v[92:93], v[238:239]
	v_pk_mul_f32 v[94:95], v[94:95], v[240:241]
	v_pk_mul_f32 v[96:97], v[96:97], v[242:243]
	v_pk_mul_f32 v[98:99], v[98:99], v[244:245]
	v_cndmask_b32_e64 v224, 0, 1, s[40:41]
	v_cmp_ne_u32_e64 s[42:43], 1, v224
	v_lshlrev_b64 v[238:239], 12, v[144:145]
	v_lshl_add_u64 v[238:239], s[28:29], 0, v[238:239]
	v_cvt_pk_bf16_f32 v224, v96, v97
	v_cvt_pk_bf16_f32 v225, v98, v99
	v_cvt_pk_bf16_f32 v226, v92, v93
	v_cvt_pk_bf16_f32 v227, v94, v95
	v_lshl_add_u64 v[238:239], v[142:143], 1, v[238:239]
	global_store_dwordx4 v[238:239], v[224:227], off offset:256 sc0 sc1
.LBB0_2030:
	s_cmp_lg_u64 s[40:41], 0
	s_cbranch_scc1 .Lm7f_1
	v_cvt_f32_ubyte0_e32 v238, v221
	v_cvt_f32_ubyte1_e32 v239, v221
	v_cvt_f32_ubyte2_e32 v240, v221
	v_cvt_f32_ubyte3_e32 v241, v221
	v_cvt_f32_ubyte0_e32 v242, v220
	v_cvt_f32_ubyte1_e32 v243, v220
	v_cvt_f32_ubyte2_e32 v244, v220
	v_cvt_f32_ubyte3_e32 v245, v220
	v_cvt_f32_ubyte0_e32 v246, v223
	v_cvt_f32_ubyte1_e32 v247, v223
	v_cvt_f32_ubyte2_e32 v248, v223
	v_cvt_f32_ubyte3_e32 v249, v223
	v_cvt_f32_ubyte0_e32 v250, v222
	v_cvt_f32_ubyte1_e32 v251, v222
	v_cvt_f32_ubyte2_e32 v252, v222
	v_cvt_f32_ubyte3_e32 v253, v222
	v_rcp_iflag_f32_e32 v246, v246
	v_rcp_iflag_f32_e32 v247, v247
	v_rcp_iflag_f32_e32 v248, v248
	v_rcp_iflag_f32_e32 v249, v249
	v_rcp_iflag_f32_e32 v250, v250
	v_rcp_iflag_f32_e32 v251, v251
	v_rcp_iflag_f32_e32 v252, v252
	v_rcp_iflag_f32_e32 v253, v253
	v_pk_mul_f32 v[238:239], v[238:239], v[246:247]
	v_pk_mul_f32 v[240:241], v[240:241], v[248:249]
	v_pk_mul_f32 v[242:243], v[242:243], v[250:251]
	v_pk_mul_f32 v[244:245], v[244:245], v[252:253]
	v_pk_mul_f32 v[116:117], v[116:117], v[238:239]
	v_pk_mul_f32 v[118:119], v[118:119], v[240:241]
	v_pk_mul_f32 v[120:121], v[120:121], v[242:243]
	v_pk_mul_f32 v[122:123], v[122:123], v[244:245]
	v_or_b32_e32 v224, 16, v144
	v_ashrrev_i32_e32 v225, 31, v224
	s_branch .LBB0_2032
.Lm7f_1:
	s_nop 1
	v_cvt_f32_ubyte0_e32 v238, v221
	v_cvt_f32_ubyte1_e32 v239, v221
	v_cvt_f32_ubyte2_e32 v240, v221
	v_cvt_f32_ubyte3_e32 v241, v221
	v_cvt_f32_ubyte0_e32 v242, v220
	v_cvt_f32_ubyte1_e32 v243, v220
	v_cvt_f32_ubyte2_e32 v244, v220
	v_cvt_f32_ubyte3_e32 v245, v220
	v_pk_mul_f32 v[238:239], v[238:239], v[232:233] op_sel:[0,1] op_sel_hi:[1,1]
	v_pk_mul_f32 v[240:241], v[240:241], v[232:233] op_sel:[0,1] op_sel_hi:[1,1]
	v_pk_mul_f32 v[242:243], v[242:243], v[232:233] op_sel:[0,1] op_sel_hi:[1,1]
	v_pk_mul_f32 v[244:245], v[244:245], v[232:233] op_sel:[0,1] op_sel_hi:[1,1]
	v_pk_mul_f32 v[116:117], v[116:117], v[238:239]
	v_pk_mul_f32 v[118:119], v[118:119], v[240:241]
	v_pk_mul_f32 v[120:121], v[120:121], v[242:243]
	v_pk_mul_f32 v[122:123], v[122:123], v[244:245]
	v_or_b32_e32 v224, 16, v144
	v_ashrrev_i32_e32 v225, 31, v224
	v_lshlrev_b64 v[226:227], 12, v[224:225]
	v_lshl_add_u64 v[226:227], s[28:29], 0, v[226:227]
	v_cvt_pk_bf16_f32 v220, v120, v121
	v_cvt_pk_bf16_f32 v221, v122, v123
	v_cvt_pk_bf16_f32 v222, v116, v117
	v_cvt_pk_bf16_f32 v223, v118, v119
	v_lshl_add_u64 v[226:227], v[142:143], 1, v[226:227]
	global_store_dwordx4 v[226:227], v[220:223], off sc0 sc1
; __device__ __forceinline__ unsigned cvt_pk_bf16(float lo, float hi) { f32x2c v = {lo, hi}; bf16x2c b = __builtin_convertvector(v, bf16x2c); return __builtin_bit_cast(unsigned, b); }
; __device__ __forceinline__ float ub0(unsigned w) { return (float)(w & 0xFFu); }
; __device__ __forceinline__ float ub1(unsigned w) { return (float)((w >> 8) & 0xFFu); }
; __device__ __forceinline__ float ub2(unsigned w) { return (float)((w >> 16) & 0xFFu); }
; __device__ __forceinline__ float ub3(unsigned w) { return (float)(w >> 24); }
;     __device__ __forceinline__ void operator()(f32x4 (&acc)[2][2][4][2], const Unit& u, int wr, int wc, int fr, int fq) const {
;     ...
;                 for (int bj = 0; bj < 2; ++bj) { const u32x2 a = gn[ai][m][bj], d = gd[ai][m][bj];
;                     const float an[8] = {ub0(a.x), ub1(a.x), ub2(a.x), ub3(a.x), ub0(a.y), ub1(a.y), ub2(a.y), ub3(a.y)};
;                     const float dn[8] = {ub0(d.x), ub1(d.x), ub2(d.x), ub3(d.x), ub0(d.y), ub1(d.y), ub2(d.y), ub3(d.y)};
;                     float f[8];
; #pragma unroll
;                     for (int k = 0; k < 8; ++k) { const float rd = __builtin_amdgcn_rcpf(dn[k]); f[k] = an[k] * (fin ? (1.0f / 255.0f) : rd); }
;                     f32x4 v0 = acc[ai][bj][m][0], v1 = acc[ai][bj][m][1];
;                     v0[0] *= f[0]; v0[1] *= f[1]; v0[2] *= f[2]; v0[3] *= f[3]; v1[0] *= f[4]; v1[1] *= f[5]; v1[2] *= f[6]; v1[3] *= f[7];
;                     acc[ai][bj][m][0] = v0; acc[ai][bj][m][1] = v1;
;                     if (fin) { u32x4 w; w.x = cvt_pk_bf16(v0[0], v0[1]); w.y = cvt_pk_bf16(v0[2], v0[3]); w.z = cvt_pk_bf16(v1[0], v1[1]); w.w = cvt_pk_bf16(v1[2], v1[3]);
;                         *(u32x4*)(MO + (size_t)(row0 + ai * HALF + m * 16) * ld + col0 + bj * HALF) = w; } }
.LBB0_2032:
	s_cmp_lg_u64 s[40:41], 0
	s_cbranch_scc1 .Lm7f_2
	v_cvt_f32_ubyte0_e32 v238, v219
	v_cvt_f32_ubyte1_e32 v239, v219
	v_cvt_f32_ubyte2_e32 v240, v219
	v_cvt_f32_ubyte3_e32 v241, v219
	v_cvt_f32_ubyte0_e32 v242, v218
	v_cvt_f32_ubyte1_e32 v243, v218
	v_cvt_f32_ubyte2_e32 v244, v218
	v_cvt_f32_ubyte3_e32 v245, v218
	v_cvt_f32_ubyte0_e32 v246, v217
	v_cvt_f32_ubyte1_e32 v247, v217
	v_cvt_f32_ubyte2_e32 v248, v217
	v_cvt_f32_ubyte3_e32 v249, v217
	v_cvt_f32_ubyte0_e32 v250, v216
	v_cvt_f32_ubyte1_e32 v251, v216
	v_cvt_f32_ubyte2_e32 v252, v216
	v_cvt_f32_ubyte3_e32 v253, v216
	v_rcp_iflag_f32_e32 v246, v246
	v_rcp_iflag_f32_e32 v247, v247
	v_rcp_iflag_f32_e32 v248, v248
	v_rcp_iflag_f32_e32 v249, v249
	v_rcp_iflag_f32_e32 v250, v250
	v_rcp_iflag_f32_e32 v251, v251
	v_rcp_iflag_f32_e32 v252, v252
	v_rcp_iflag_f32_e32 v253, v253
	v_pk_mul_f32 v[238:239], v[238:239], v[246:247]
	v_pk_mul_f32 v[240:241], v[240:241], v[248:249]
	v_pk_mul_f32 v[242:243], v[242:243], v[250:251]
	v_pk_mul_f32 v[244:245], v[244:245], v[252:253]
	v_pk_mul_f32 v[84:85], v[84:85], v[238:239]
	v_pk_mul_f32 v[86:87], v[86:87], v[240:241]
	v_pk_mul_f32 v[88:89], v[88:89], v[242:243]
	v_pk_mul_f32 v[90:91], v[90:91], v[244:245]
	s_branch .LBB0_2034
.Lm7f_2:
	s_nop 1
	v_cvt_f32_ubyte0_e32 v238, v219
	v_cvt_f32_ubyte1_e32 v239, v219
	v_cvt_f32_ubyte2_e32 v240, v219
	v_cvt_f32_ubyte3_e32 v241, v219
	v_cvt_f32_ubyte0_e32 v242, v218
	v_cvt_f32_ubyte1_e32 v243, v218
	v_cvt_f32_ubyte2_e32 v244, v218
	v_cvt_f32_ubyte3_e32 v245, v218
	v_pk_mul_f32 v[238:239], v[238:239], v[232:233] op_sel:[0,1] op_sel_hi:[1,1]
	v_pk_mul_f32 v[240:241], v[240:241], v[232:233] op_sel:[0,1] op_sel_hi:[1,1]
	v_pk_mul_f32 v[242:243], v[242:243], v[232:233] op_sel:[0,1] op_sel_hi:[1,1]
	v_pk_mul_f32 v[244:245], v[244:245], v[232:233] op_sel:[0,1] op_sel_hi:[1,1]
	v_pk_mul_f32 v[84:85], v[84:85], v[238:239]
	v_pk_mul_f32 v[86:87], v[86:87], v[240:241]
	v_pk_mul_f32 v[88:89], v[88:89], v[242:243]
	v_pk_mul_f32 v[90:91], v[90:91], v[244:245]
	v_lshlrev_b64 v[220:221], 12, v[224:225]
	v_lshl_add_u64 v[220:221], s[28:29], 0, v[220:221]
	v_cvt_pk_bf16_f32 v216, v88, v89
	v_cvt_pk_bf16_f32 v217, v90, v91
	v_cvt_pk_bf16_f32 v218, v84, v85
	v_cvt_pk_bf16_f32 v219, v86, v87
	v_lshl_add_u64 v[220:221], v[142:143], 1, v[220:221]
	global_store_dwordx4 v[220:221], v[216:219], off offset:256 sc0 sc1
.LBB0_2034:
	s_cmp_lg_u64 s[40:41], 0
	s_cbranch_scc1 .Lm7f_3
	v_cvt_f32_ubyte0_e32 v238, v213
	v_cvt_f32_ubyte1_e32 v239, v213
	v_cvt_f32_ubyte2_e32 v240, v213
	v_cvt_f32_ubyte3_e32 v241, v213
	v_cvt_f32_ubyte0_e32 v242, v212
	v_cvt_f32_ubyte1_e32 v243, v212
	v_cvt_f32_ubyte2_e32 v244, v212
	v_cvt_f32_ubyte3_e32 v245, v212
	v_cvt_f32_ubyte0_e32 v246, v215
	v_cvt_f32_ubyte1_e32 v247, v215
	v_cvt_f32_ubyte2_e32 v248, v215
	v_cvt_f32_ubyte3_e32 v249, v215
	v_cvt_f32_ubyte0_e32 v250, v214
	v_cvt_f32_ubyte1_e32 v251, v214
	v_cvt_f32_ubyte2_e32 v252, v214
	v_cvt_f32_ubyte3_e32 v253, v214
	v_rcp_iflag_f32_e32 v246, v246
	v_rcp_iflag_f32_e32 v247, v247
	v_rcp_iflag_f32_e32 v248, v248
	v_rcp_iflag_f32_e32 v249, v249
	v_rcp_iflag_f32_e32 v250, v250
	v_rcp_iflag_f32_e32 v251, v251
	v_rcp_iflag_f32_e32 v252, v252
	v_rcp_iflag_f32_e32 v253, v253
	v_pk_mul_f32 v[238:239], v[238:239], v[246:247]
	v_pk_mul_f32 v[240:241], v[240:241], v[248:249]
	v_pk_mul_f32 v[242:243], v[242:243], v[250:251]
	v_pk_mul_f32 v[244:245], v[244:245], v[252:253]
	v_pk_mul_f32 v[108:109], v[108:109], v[238:239]
	v_pk_mul_f32 v[110:111], v[110:111], v[240:241]
	v_pk_mul_f32 v[112:113], v[112:113], v[242:243]
	v_pk_mul_f32 v[114:115], v[114:115], v[244:245]
	v_or_b32_e32 v216, 32, v144
	v_ashrrev_i32_e32 v217, 31, v216
	s_branch .LBB0_2036
.Lm7f_3:
	s_nop 1
	v_cvt_f32_ubyte0_e32 v238, v213
	v_cvt_f32_ubyte1_e32 v239, v213
	v_cvt_f32_ubyte2_e32 v240, v213
	v_cvt_f32_ubyte3_e32 v241, v213
	v_cvt_f32_ubyte0_e32 v242, v212
	v_cvt_f32_ubyte1_e32 v243, v212
	v_cvt_f32_ubyte2_e32 v244, v212
	v_cvt_f32_ubyte3_e32 v245, v212
	v_pk_mul_f32 v[238:239], v[238:239], v[232:233] op_sel:[0,1] op_sel_hi:[1,1]
	v_pk_mul_f32 v[240:241], v[240:241], v[232:233] op_sel:[0,1] op_sel_hi:[1,1]
	v_pk_mul_f32 v[242:243], v[242:243], v[232:233] op_sel:[0,1] op_sel_hi:[1,1]
	v_pk_mul_f32 v[244:245], v[244:245], v[232:233] op_sel:[0,1] op_sel_hi:[1,1]
	v_pk_mul_f32 v[108:109], v[108:109], v[238:239]
	v_pk_mul_f32 v[110:111], v[110:111], v[240:241]
	v_pk_mul_f32 v[112:113], v[112:113], v[242:243]
	v_pk_mul_f32 v[114:115], v[114:115], v[244:245]
	v_or_b32_e32 v216, 32, v144
	v_ashrrev_i32_e32 v217, 31, v216
	v_lshlrev_b64 v[218:219], 12, v[216:217]
	v_lshl_add_u64 v[218:219], s[28:29], 0, v[218:219]
	v_cvt_pk_bf16_f32 v212, v112, v113
	v_cvt_pk_bf16_f32 v213, v114, v115
	v_cvt_pk_bf16_f32 v214, v108, v109
	v_cvt_pk_bf16_f32 v215, v110, v111
	v_lshl_add_u64 v[218:219], v[142:143], 1, v[218:219]
	global_store_dwordx4 v[218:219], v[212:215], off sc0 sc1
.LBB0_2036:
	s_cmp_lg_u64 s[40:41], 0
	s_cbranch_scc1 .Lm7f_4
	v_cvt_f32_ubyte0_e32 v238, v211
	v_cvt_f32_ubyte1_e32 v239, v211
	v_cvt_f32_ubyte2_e32 v240, v211
	v_cvt_f32_ubyte3_e32 v241, v211
	v_cvt_f32_ubyte0_e32 v242, v210
	v_cvt_f32_ubyte1_e32 v243, v210
	v_cvt_f32_ubyte2_e32 v244, v210
	v_cvt_f32_ubyte3_e32 v245, v210
	v_cvt_f32_ubyte0_e32 v246, v209
	v_cvt_f32_ubyte1_e32 v247, v209
	v_cvt_f32_ubyte2_e32 v248, v209
	v_cvt_f32_ubyte3_e32 v249, v209
	v_cvt_f32_ubyte0_e32 v250, v208
	v_cvt_f32_ubyte1_e32 v251, v208
	v_cvt_f32_ubyte2_e32 v252, v208
	v_cvt_f32_ubyte3_e32 v253, v208
	v_rcp_iflag_f32_e32 v246, v246
	v_rcp_iflag_f32_e32 v247, v247
	v_rcp_iflag_f32_e32 v248, v248
	v_rcp_iflag_f32_e32 v249, v249
	v_rcp_iflag_f32_e32 v250, v250
	v_rcp_iflag_f32_e32 v251, v251
	v_rcp_iflag_f32_e32 v252, v252
	v_rcp_iflag_f32_e32 v253, v253
	v_pk_mul_f32 v[238:239], v[238:239], v[246:247]
	v_pk_mul_f32 v[240:241], v[240:241], v[248:249]
	v_pk_mul_f32 v[242:243], v[242:243], v[250:251]
	v_pk_mul_f32 v[244:245], v[244:245], v[252:253]
	v_pk_mul_f32 v[76:77], v[76:77], v[238:239]
	v_pk_mul_f32 v[78:79], v[78:79], v[240:241]
	v_pk_mul_f32 v[80:81], v[80:81], v[242:243]
	v_pk_mul_f32 v[82:83], v[82:83], v[244:245]
	s_branch .LBB0_2038
; __device__ __forceinline__ unsigned cvt_pk_bf16(float lo, float hi) { f32x2c v = {lo, hi}; bf16x2c b = __builtin_convertvector(v, bf16x2c); return __builtin_bit_cast(unsigned, b); }
; __device__ __forceinline__ float ub0(unsigned w) { return (float)(w & 0xFFu); }
; __device__ __forceinline__ float ub1(unsigned w) { return (float)((w >> 8) & 0xFFu); }
; __device__ __forceinline__ float ub2(unsigned w) { return (float)((w >> 16) & 0xFFu); }
; __device__ __forceinline__ float ub3(unsigned w) { return (float)(w >> 24); }
;     __device__ __forceinline__ void operator()(f32x4 (&acc)[2][2][4][2], const Unit& u, int wr, int wc, int fr, int fq) const {
;     ...
;                 for (int bj = 0; bj < 2; ++bj) { const u32x2 a = gn[ai][m][bj], d = gd[ai][m][bj];
;                     const float an[8] = {ub0(a.x), ub1(a.x), ub2(a.x), ub3(a.x), ub0(a.y), ub1(a.y), ub2(a.y), ub3(a.y)};
;                     const float dn[8] = {ub0(d.x), ub1(d.x), ub2(d.x), ub3(d.x), ub0(d.y), ub1(d.y), ub2(d.y), ub3(d.y)};
;                     float f[8];
; #pragma unroll
;                     for (int k = 0; k < 8; ++k) { const float rd = __builtin_amdgcn_rcpf(dn[k]); f[k] = an[k] * (fin ? (1.0f / 255.0f) : rd); }
;                     f32x4 v0 = acc[ai][bj][m][0], v1 = acc[ai][bj][m][1];
;                     v0[0] *= f[0]; v0[1] *= f[1]; v0[2] *= f[2]; v0[3] *= f[3]; v1[0] *= f[4]; v1[1] *= f[5]; v1[2] *= f[6]; v1[3] *= f[7];
;                     acc[ai][bj][m][0] = v0; acc[ai][bj][m][1] = v1;
;                     if (fin) { u32x4 w; w.x = cvt_pk_bf16(v0[0], v0[1]); w.y = cvt_pk_bf16(v0[2], v0[3]); w.z = cvt_pk_bf16(v1[0], v1[1]); w.w = cvt_pk_bf16(v1[2], v1[3]);
;                         *(u32x4*)(MO + (size_t)(row0 + ai * HALF + m * 16) * ld + col0 + bj * HALF) = w; } }
.Lm7f_4:
	s_nop 1
	v_cvt_f32_ubyte0_e32 v238, v211
	v_cvt_f32_ubyte1_e32 v239, v211
	v_cvt_f32_ubyte2_e32 v240, v211
	v_cvt_f32_ubyte3_e32 v241, v211
	v_cvt_f32_ubyte0_e32 v242, v210
	v_cvt_f32_ubyte1_e32 v243, v210
	v_cvt_f32_ubyte2_e32 v244, v210
	v_cvt_f32_ubyte3_e32 v245, v210
	v_pk_mul_f32 v[238:239], v[238:239], v[232:233] op_sel:[0,1] op_sel_hi:[1,1]
	v_pk_mul_f32 v[240:241], v[240:241], v[232:233] op_sel:[0,1] op_sel_hi:[1,1]
	v_pk_mul_f32 v[242:243], v[242:243], v[232:233] op_sel:[0,1] op_sel_hi:[1,1]
	v_pk_mul_f32 v[244:245], v[244:245], v[232:233] op_sel:[0,1] op_sel_hi:[1,1]
	v_pk_mul_f32 v[76:77], v[76:77], v[238:239]
	v_pk_mul_f32 v[78:79], v[78:79], v[240:241]
	v_pk_mul_f32 v[80:81], v[80:81], v[242:243]
	v_pk_mul_f32 v[82:83], v[82:83], v[244:245]
	v_lshlrev_b64 v[212:213], 12, v[216:217]
	v_lshl_add_u64 v[212:213], s[28:29], 0, v[212:213]
	v_cvt_pk_bf16_f32 v208, v80, v81
	v_cvt_pk_bf16_f32 v209, v82, v83
	v_cvt_pk_bf16_f32 v210, v76, v77
	v_cvt_pk_bf16_f32 v211, v78, v79
	v_lshl_add_u64 v[212:213], v[142:143], 1, v[212:213]
	global_store_dwordx4 v[212:213], v[208:211], off offset:256 sc0 sc1
.LBB0_2038:
	s_waitcnt vmcnt(18)
	s_cmp_lg_u64 s[40:41], 0
	s_cbranch_scc1 .Lm7f_5
	v_cvt_f32_ubyte0_e32 v238, v205
	v_cvt_f32_ubyte1_e32 v239, v205
	v_cvt_f32_ubyte2_e32 v240, v205
	v_cvt_f32_ubyte3_e32 v241, v205
	v_cvt_f32_ubyte0_e32 v242, v204
	v_cvt_f32_ubyte1_e32 v243, v204
	v_cvt_f32_ubyte2_e32 v244, v204
	v_cvt_f32_ubyte3_e32 v245, v204
	v_cvt_f32_ubyte0_e32 v246, v207
	v_cvt_f32_ubyte1_e32 v247, v207
	v_cvt_f32_ubyte2_e32 v248, v207
	v_cvt_f32_ubyte3_e32 v249, v207
	v_cvt_f32_ubyte0_e32 v250, v206
	v_cvt_f32_ubyte1_e32 v251, v206
	v_cvt_f32_ubyte2_e32 v252, v206
	v_cvt_f32_ubyte3_e32 v253, v206
	v_rcp_iflag_f32_e32 v246, v246
	v_rcp_iflag_f32_e32 v247, v247
	v_rcp_iflag_f32_e32 v248, v248
	v_rcp_iflag_f32_e32 v249, v249
	v_rcp_iflag_f32_e32 v250, v250
	v_rcp_iflag_f32_e32 v251, v251
	v_rcp_iflag_f32_e32 v252, v252
	v_rcp_iflag_f32_e32 v253, v253
	v_pk_mul_f32 v[238:239], v[238:239], v[246:247]
	v_pk_mul_f32 v[240:241], v[240:241], v[248:249]
	v_pk_mul_f32 v[242:243], v[242:243], v[250:251]
	v_pk_mul_f32 v[244:245], v[244:245], v[252:253]
	v_pk_mul_f32 v[100:101], v[100:101], v[238:239]
	v_pk_mul_f32 v[102:103], v[102:103], v[240:241]
	v_pk_mul_f32 v[104:105], v[104:105], v[242:243]
	v_pk_mul_f32 v[106:107], v[106:107], v[244:245]
	v_or_b32_e32 v208, 48, v144
	v_ashrrev_i32_e32 v209, 31, v208
	s_branch .LBB0_2040
.Lm7f_5:
	s_nop 1
	v_cvt_f32_ubyte0_e32 v238, v205
	v_cvt_f32_ubyte1_e32 v239, v205
	v_cvt_f32_ubyte2_e32 v240, v205
	v_cvt_f32_ubyte3_e32 v241, v205
	v_cvt_f32_ubyte0_e32 v242, v204
	v_cvt_f32_ubyte1_e32 v243, v204
	v_cvt_f32_ubyte2_e32 v244, v204
	v_cvt_f32_ubyte3_e32 v245, v204
	v_pk_mul_f32 v[238:239], v[238:239], v[232:233] op_sel:[0,1] op_sel_hi:[1,1]
	v_pk_mul_f32 v[240:241], v[240:241], v[232:233] op_sel:[0,1] op_sel_hi:[1,1]
	v_pk_mul_f32 v[242:243], v[242:243], v[232:233] op_sel:[0,1] op_sel_hi:[1,1]
	v_pk_mul_f32 v[244:245], v[244:245], v[232:233] op_sel:[0,1] op_sel_hi:[1,1]
	v_pk_mul_f32 v[100:101], v[100:101], v[238:239]
	v_pk_mul_f32 v[102:103], v[102:103], v[240:241]
	v_pk_mul_f32 v[104:105], v[104:105], v[242:243]
	v_pk_mul_f32 v[106:107], v[106:107], v[244:245]
	v_or_b32_e32 v208, 48, v144
	v_ashrrev_i32_e32 v209, 31, v208
	v_lshlrev_b64 v[210:211], 12, v[208:209]
	v_lshl_add_u64 v[210:211], s[28:29], 0, v[210:211]
	v_cvt_pk_bf16_f32 v204, v104, v105
	v_cvt_pk_bf16_f32 v205, v106, v107
	v_cvt_pk_bf16_f32 v206, v100, v101
	v_cvt_pk_bf16_f32 v207, v102, v103
	v_lshl_add_u64 v[210:211], v[142:143], 1, v[210:211]
	global_store_dwordx4 v[210:211], v[204:207], off sc0 sc1
.LBB0_2040:
	s_waitcnt vmcnt(16)
	s_cmp_lg_u64 s[40:41], 0
	s_cbranch_scc1 .Lm7f_6
	v_cvt_f32_ubyte0_e32 v238, v203
	v_cvt_f32_ubyte1_e32 v239, v203
	v_cvt_f32_ubyte2_e32 v240, v203
	v_cvt_f32_ubyte3_e32 v241, v203
	v_cvt_f32_ubyte0_e32 v242, v202
	v_cvt_f32_ubyte1_e32 v243, v202
	v_cvt_f32_ubyte2_e32 v244, v202
	v_cvt_f32_ubyte3_e32 v245, v202
	v_cvt_f32_ubyte0_e32 v246, v201
	v_cvt_f32_ubyte1_e32 v247, v201
	v_cvt_f32_ubyte2_e32 v248, v201
	v_cvt_f32_ubyte3_e32 v249, v201
	v_cvt_f32_ubyte0_e32 v250, v200
	v_cvt_f32_ubyte1_e32 v251, v200
	v_cvt_f32_ubyte2_e32 v252, v200
	v_cvt_f32_ubyte3_e32 v253, v200
	v_rcp_iflag_f32_e32 v246, v246
	v_rcp_iflag_f32_e32 v247, v247
	v_rcp_iflag_f32_e32 v248, v248
	v_rcp_iflag_f32_e32 v249, v249
	v_rcp_iflag_f32_e32 v250, v250
	v_rcp_iflag_f32_e32 v251, v251
	v_rcp_iflag_f32_e32 v252, v252
	v_rcp_iflag_f32_e32 v253, v253
	v_pk_mul_f32 v[238:239], v[238:239], v[246:247]
	v_pk_mul_f32 v[240:241], v[240:241], v[248:249]
	v_pk_mul_f32 v[242:243], v[242:243], v[250:251]
	v_pk_mul_f32 v[244:245], v[244:245], v[252:253]
	v_pk_mul_f32 v[68:69], v[68:69], v[238:239]
	v_pk_mul_f32 v[70:71], v[70:71], v[240:241]
	v_pk_mul_f32 v[72:73], v[72:73], v[242:243]
	v_pk_mul_f32 v[74:75], v[74:75], v[244:245]
	s_branch .LBB0_2042
.Lm7f_6:
	s_nop 1
	v_cvt_f32_ubyte0_e32 v238, v203
	v_cvt_f32_ubyte1_e32 v239, v203
	v_cvt_f32_ubyte2_e32 v240, v203
	v_cvt_f32_ubyte3_e32 v241, v203
	v_cvt_f32_ubyte0_e32 v242, v202
	v_cvt_f32_ubyte1_e32 v243, v202
	v_cvt_f32_ubyte2_e32 v244, v202
	v_cvt_f32_ubyte3_e32 v245, v202
	v_pk_mul_f32 v[238:239], v[238:239], v[232:233] op_sel:[0,1] op_sel_hi:[1,1]
	v_pk_mul_f32 v[240:241], v[240:241], v[232:233] op_sel:[0,1] op_sel_hi:[1,1]
	v_pk_mul_f32 v[242:243], v[242:243], v[232:233] op_sel:[0,1] op_sel_hi:[1,1]
	v_pk_mul_f32 v[244:245], v[244:245], v[232:233] op_sel:[0,1] op_sel_hi:[1,1]
	v_pk_mul_f32 v[68:69], v[68:69], v[238:239]
	v_pk_mul_f32 v[70:71], v[70:71], v[240:241]
	v_pk_mul_f32 v[72:73], v[72:73], v[242:243]
	v_pk_mul_f32 v[74:75], v[74:75], v[244:245]
	v_lshlrev_b64 v[204:205], 12, v[208:209]
	v_lshl_add_u64 v[204:205], s[28:29], 0, v[204:205]
	v_cvt_pk_bf16_f32 v200, v72, v73
	v_cvt_pk_bf16_f32 v201, v74, v75
	v_cvt_pk_bf16_f32 v202, v68, v69
	v_cvt_pk_bf16_f32 v203, v70, v71
	v_lshl_add_u64 v[204:205], v[142:143], 1, v[204:205]
	global_store_dwordx4 v[204:205], v[200:203], off offset:256 sc0 sc1
; __device__ __forceinline__ unsigned cvt_pk_bf16(float lo, float hi) { f32x2c v = {lo, hi}; bf16x2c b = __builtin_convertvector(v, bf16x2c); return __builtin_bit_cast(unsigned, b); }
; __device__ __forceinline__ float ub0(unsigned w) { return (float)(w & 0xFFu); }
; __device__ __forceinline__ float ub1(unsigned w) { return (float)((w >> 8) & 0xFFu); }
; __device__ __forceinline__ float ub2(unsigned w) { return (float)((w >> 16) & 0xFFu); }
; __device__ __forceinline__ float ub3(unsigned w) { return (float)(w >> 24); }
;     __device__ __forceinline__ void operator()(f32x4 (&acc)[2][2][4][2], const Unit& u, int wr, int wc, int fr, int fq) const {
;     ...
;                 for (int bj = 0; bj < 2; ++bj) { const u32x2 a = gn[ai][m][bj], d = gd[ai][m][bj];
;                     const float an[8] = {ub0(a.x), ub1(a.x), ub2(a.x), ub3(a.x), ub0(a.y), ub1(a.y), ub2(a.y), ub3(a.y)};
;                     const float dn[8] = {ub0(d.x), ub1(d.x), ub2(d.x), ub3(d.x), ub0(d.y), ub1(d.y), ub2(d.y), ub3(d.y)};
;                     float f[8];
; #pragma unroll
;                     for (int k = 0; k < 8; ++k) { const float rd = __builtin_amdgcn_rcpf(dn[k]); f[k] = an[k] * (fin ? (1.0f / 255.0f) : rd); }
;                     f32x4 v0 = acc[ai][bj][m][0], v1 = acc[ai][bj][m][1];
;                     v0[0] *= f[0]; v0[1] *= f[1]; v0[2] *= f[2]; v0[3] *= f[3]; v1[0] *= f[4]; v1[1] *= f[5]; v1[2] *= f[6]; v1[3] *= f[7];
;                     acc[ai][bj][m][0] = v0; acc[ai][bj][m][1] = v1;
;                     if (fin) { u32x4 w; w.x = cvt_pk_bf16(v0[0], v0[1]); w.y = cvt_pk_bf16(v0[2], v0[3]); w.z = cvt_pk_bf16(v1[0], v1[1]); w.w = cvt_pk_bf16(v1[2], v1[3]);
;                         *(u32x4*)(MO + (size_t)(row0 + ai * HALF + m * 16) * ld + col0 + bj * HALF) = w; } }
.LBB0_2042:
	s_waitcnt vmcnt(14)
	s_cmp_lg_u64 s[40:41], 0
	s_cbranch_scc1 .Lm7f_7
	v_cvt_f32_ubyte0_e32 v238, v197
	v_cvt_f32_ubyte1_e32 v239, v197
	v_cvt_f32_ubyte2_e32 v240, v197
	v_cvt_f32_ubyte3_e32 v241, v197
	v_cvt_f32_ubyte0_e32 v242, v196
	v_cvt_f32_ubyte1_e32 v243, v196
	v_cvt_f32_ubyte2_e32 v244, v196
	v_cvt_f32_ubyte3_e32 v245, v196
	v_cvt_f32_ubyte0_e32 v246, v199
	v_cvt_f32_ubyte1_e32 v247, v199
	v_cvt_f32_ubyte2_e32 v248, v199
	v_cvt_f32_ubyte3_e32 v249, v199
	v_cvt_f32_ubyte0_e32 v250, v198
	v_cvt_f32_ubyte1_e32 v251, v198
	v_cvt_f32_ubyte2_e32 v252, v198
	v_cvt_f32_ubyte3_e32 v253, v198
	v_rcp_iflag_f32_e32 v246, v246
	v_rcp_iflag_f32_e32 v247, v247
	v_rcp_iflag_f32_e32 v248, v248
	v_rcp_iflag_f32_e32 v249, v249
	v_rcp_iflag_f32_e32 v250, v250
	v_rcp_iflag_f32_e32 v251, v251
	v_rcp_iflag_f32_e32 v252, v252
	v_rcp_iflag_f32_e32 v253, v253
	v_pk_mul_f32 v[238:239], v[238:239], v[246:247]
	v_pk_mul_f32 v[240:241], v[240:241], v[248:249]
	v_pk_mul_f32 v[242:243], v[242:243], v[250:251]
	v_pk_mul_f32 v[244:245], v[244:245], v[252:253]
	v_pk_mul_f32 v[60:61], v[60:61], v[238:239]
	v_pk_mul_f32 v[62:63], v[62:63], v[240:241]
	v_pk_mul_f32 v[64:65], v[64:65], v[242:243]
	v_pk_mul_f32 v[66:67], v[66:67], v[244:245]
	v_add_u32_e32 v200, 0x80, v144
	v_ashrrev_i32_e32 v201, 31, v200
	s_branch .LBB0_2044
.Lm7f_7:
	s_nop 1
	v_cvt_f32_ubyte0_e32 v238, v197
	v_cvt_f32_ubyte1_e32 v239, v197
	v_cvt_f32_ubyte2_e32 v240, v197
	v_cvt_f32_ubyte3_e32 v241, v197
	v_cvt_f32_ubyte0_e32 v242, v196
	v_cvt_f32_ubyte1_e32 v243, v196
	v_cvt_f32_ubyte2_e32 v244, v196
	v_cvt_f32_ubyte3_e32 v245, v196
	v_pk_mul_f32 v[238:239], v[238:239], v[232:233] op_sel:[0,1] op_sel_hi:[1,1]
	v_pk_mul_f32 v[240:241], v[240:241], v[232:233] op_sel:[0,1] op_sel_hi:[1,1]
	v_pk_mul_f32 v[242:243], v[242:243], v[232:233] op_sel:[0,1] op_sel_hi:[1,1]
	v_pk_mul_f32 v[244:245], v[244:245], v[232:233] op_sel:[0,1] op_sel_hi:[1,1]
	v_pk_mul_f32 v[60:61], v[60:61], v[238:239]
	v_pk_mul_f32 v[62:63], v[62:63], v[240:241]
	v_pk_mul_f32 v[64:65], v[64:65], v[242:243]
	v_pk_mul_f32 v[66:67], v[66:67], v[244:245]
	v_add_u32_e32 v200, 0x80, v144
	v_ashrrev_i32_e32 v201, 31, v200
	v_lshlrev_b64 v[202:203], 12, v[200:201]
	v_lshl_add_u64 v[202:203], s[28:29], 0, v[202:203]
	v_cvt_pk_bf16_f32 v196, v64, v65
	v_cvt_pk_bf16_f32 v197, v66, v67
	v_cvt_pk_bf16_f32 v198, v60, v61
	v_cvt_pk_bf16_f32 v199, v62, v63
	v_lshl_add_u64 v[202:203], v[142:143], 1, v[202:203]
	global_store_dwordx4 v[202:203], v[196:199], off sc0 sc1
.LBB0_2044:
	s_waitcnt vmcnt(12)
	s_cmp_lg_u64 s[40:41], 0
	s_cbranch_scc1 .Lm7f_8
	v_cvt_f32_ubyte0_e32 v238, v195
	v_cvt_f32_ubyte1_e32 v239, v195
	v_cvt_f32_ubyte2_e32 v240, v195
	v_cvt_f32_ubyte3_e32 v241, v195
	v_cvt_f32_ubyte0_e32 v242, v194
	v_cvt_f32_ubyte1_e32 v243, v194
	v_cvt_f32_ubyte2_e32 v244, v194
	v_cvt_f32_ubyte3_e32 v245, v194
	v_cvt_f32_ubyte0_e32 v246, v193
	v_cvt_f32_ubyte1_e32 v247, v193
	v_cvt_f32_ubyte2_e32 v248, v193
	v_cvt_f32_ubyte3_e32 v249, v193
	v_cvt_f32_ubyte0_e32 v250, v192
	v_cvt_f32_ubyte1_e32 v251, v192
	v_cvt_f32_ubyte2_e32 v252, v192
	v_cvt_f32_ubyte3_e32 v253, v192
	v_rcp_iflag_f32_e32 v246, v246
	v_rcp_iflag_f32_e32 v247, v247
	v_rcp_iflag_f32_e32 v248, v248
	v_rcp_iflag_f32_e32 v249, v249
	v_rcp_iflag_f32_e32 v250, v250
	v_rcp_iflag_f32_e32 v251, v251
	v_rcp_iflag_f32_e32 v252, v252
	v_rcp_iflag_f32_e32 v253, v253
	v_pk_mul_f32 v[238:239], v[238:239], v[246:247]
	v_pk_mul_f32 v[240:241], v[240:241], v[248:249]
	v_pk_mul_f32 v[242:243], v[242:243], v[250:251]
	v_pk_mul_f32 v[244:245], v[244:245], v[252:253]
	v_pk_mul_f32 v[26:27], v[26:27], v[238:239]
	v_pk_mul_f32 v[28:29], v[28:29], v[240:241]
	v_pk_mul_f32 v[30:31], v[30:31], v[242:243]
	v_pk_mul_f32 v[32:33], v[32:33], v[244:245]
	s_branch .LBB0_2046
.Lm7f_8:
	s_nop 1
	v_cvt_f32_ubyte0_e32 v238, v195
	v_cvt_f32_ubyte1_e32 v239, v195
	v_cvt_f32_ubyte2_e32 v240, v195
	v_cvt_f32_ubyte3_e32 v241, v195
	v_cvt_f32_ubyte0_e32 v242, v194
	v_cvt_f32_ubyte1_e32 v243, v194
	v_cvt_f32_ubyte2_e32 v244, v194
	v_cvt_f32_ubyte3_e32 v245, v194
	v_pk_mul_f32 v[238:239], v[238:239], v[232:233] op_sel:[0,1] op_sel_hi:[1,1]
	v_pk_mul_f32 v[240:241], v[240:241], v[232:233] op_sel:[0,1] op_sel_hi:[1,1]
	v_pk_mul_f32 v[242:243], v[242:243], v[232:233] op_sel:[0,1] op_sel_hi:[1,1]
	v_pk_mul_f32 v[244:245], v[244:245], v[232:233] op_sel:[0,1] op_sel_hi:[1,1]
	v_pk_mul_f32 v[26:27], v[26:27], v[238:239]
	v_pk_mul_f32 v[28:29], v[28:29], v[240:241]
	v_pk_mul_f32 v[30:31], v[30:31], v[242:243]
	v_pk_mul_f32 v[32:33], v[32:33], v[244:245]
	v_lshlrev_b64 v[196:197], 12, v[200:201]
	v_lshl_add_u64 v[196:197], s[28:29], 0, v[196:197]
	v_cvt_pk_bf16_f32 v192, v30, v31
	v_cvt_pk_bf16_f32 v193, v32, v33
	v_cvt_pk_bf16_f32 v194, v26, v27
	v_cvt_pk_bf16_f32 v195, v28, v29
	v_lshl_add_u64 v[196:197], v[142:143], 1, v[196:197]
	global_store_dwordx4 v[196:197], v[192:195], off offset:256 sc0 sc1
.LBB0_2046:
	s_waitcnt vmcnt(10)
	s_cmp_lg_u64 s[40:41], 0
	s_cbranch_scc1 .Lm7f_9
	v_cvt_f32_ubyte0_e32 v238, v189
	v_cvt_f32_ubyte1_e32 v239, v189
	v_cvt_f32_ubyte2_e32 v240, v189
	v_cvt_f32_ubyte3_e32 v241, v189
	v_cvt_f32_ubyte0_e32 v242, v188
	v_cvt_f32_ubyte1_e32 v243, v188
	v_cvt_f32_ubyte2_e32 v244, v188
	v_cvt_f32_ubyte3_e32 v245, v188
	v_cvt_f32_ubyte0_e32 v246, v191
	v_cvt_f32_ubyte1_e32 v247, v191
	v_cvt_f32_ubyte2_e32 v248, v191
	v_cvt_f32_ubyte3_e32 v249, v191
	v_cvt_f32_ubyte0_e32 v250, v190
	v_cvt_f32_ubyte1_e32 v251, v190
	v_cvt_f32_ubyte2_e32 v252, v190
	v_cvt_f32_ubyte3_e32 v253, v190
	v_rcp_iflag_f32_e32 v246, v246
	v_rcp_iflag_f32_e32 v247, v247
	v_rcp_iflag_f32_e32 v248, v248
	v_rcp_iflag_f32_e32 v249, v249
	v_rcp_iflag_f32_e32 v250, v250
	v_rcp_iflag_f32_e32 v251, v251
	v_rcp_iflag_f32_e32 v252, v252
	v_rcp_iflag_f32_e32 v253, v253
	v_pk_mul_f32 v[238:239], v[238:239], v[246:247]
	v_pk_mul_f32 v[240:241], v[240:241], v[248:249]
	v_pk_mul_f32 v[242:243], v[242:243], v[250:251]
	v_pk_mul_f32 v[244:245], v[244:245], v[252:253]
	v_pk_mul_f32 v[52:53], v[52:53], v[238:239]
	v_pk_mul_f32 v[54:55], v[54:55], v[240:241]
	v_pk_mul_f32 v[56:57], v[56:57], v[242:243]
	v_pk_mul_f32 v[58:59], v[58:59], v[244:245]
	v_add_u32_e32 v192, 0x90, v144
	v_ashrrev_i32_e32 v193, 31, v192
	s_branch .LBB0_2048
; __device__ __forceinline__ unsigned cvt_pk_bf16(float lo, float hi) { f32x2c v = {lo, hi}; bf16x2c b = __builtin_convertvector(v, bf16x2c); return __builtin_bit_cast(unsigned, b); }
; __device__ __forceinline__ float ub0(unsigned w) { return (float)(w & 0xFFu); }
; __device__ __forceinline__ float ub1(unsigned w) { return (float)((w >> 8) & 0xFFu); }
; __device__ __forceinline__ float ub2(unsigned w) { return (float)((w >> 16) & 0xFFu); }
; __device__ __forceinline__ float ub3(unsigned w) { return (float)(w >> 24); }
;     __device__ __forceinline__ void operator()(f32x4 (&acc)[2][2][4][2], const Unit& u, int wr, int wc, int fr, int fq) const {
;     ...
;                 for (int bj = 0; bj < 2; ++bj) { const u32x2 a = gn[ai][m][bj], d = gd[ai][m][bj];
;                     const float an[8] = {ub0(a.x), ub1(a.x), ub2(a.x), ub3(a.x), ub0(a.y), ub1(a.y), ub2(a.y), ub3(a.y)};
;                     const float dn[8] = {ub0(d.x), ub1(d.x), ub2(d.x), ub3(d.x), ub0(d.y), ub1(d.y), ub2(d.y), ub3(d.y)};
;                     float f[8];
; #pragma unroll
;                     for (int k = 0; k < 8; ++k) { const float rd = __builtin_amdgcn_rcpf(dn[k]); f[k] = an[k] * (fin ? (1.0f / 255.0f) : rd); }
;                     f32x4 v0 = acc[ai][bj][m][0], v1 = acc[ai][bj][m][1];
;                     v0[0] *= f[0]; v0[1] *= f[1]; v0[2] *= f[2]; v0[3] *= f[3]; v1[0] *= f[4]; v1[1] *= f[5]; v1[2] *= f[6]; v1[3] *= f[7];
;                     acc[ai][bj][m][0] = v0; acc[ai][bj][m][1] = v1;
;                     if (fin) { u32x4 w; w.x = cvt_pk_bf16(v0[0], v0[1]); w.y = cvt_pk_bf16(v0[2], v0[3]); w.z = cvt_pk_bf16(v1[0], v1[1]); w.w = cvt_pk_bf16(v1[2], v1[3]);
;                         *(u32x4*)(MO + (size_t)(row0 + ai * HALF + m * 16) * ld + col0 + bj * HALF) = w; } }
.Lm7f_9:
	s_nop 1
	v_cvt_f32_ubyte0_e32 v238, v189
	v_cvt_f32_ubyte1_e32 v239, v189
	v_cvt_f32_ubyte2_e32 v240, v189
	v_cvt_f32_ubyte3_e32 v241, v189
	v_cvt_f32_ubyte0_e32 v242, v188
	v_cvt_f32_ubyte1_e32 v243, v188
	v_cvt_f32_ubyte2_e32 v244, v188
	v_cvt_f32_ubyte3_e32 v245, v188
	v_pk_mul_f32 v[238:239], v[238:239], v[232:233] op_sel:[0,1] op_sel_hi:[1,1]
	v_pk_mul_f32 v[240:241], v[240:241], v[232:233] op_sel:[0,1] op_sel_hi:[1,1]
	v_pk_mul_f32 v[242:243], v[242:243], v[232:233] op_sel:[0,1] op_sel_hi:[1,1]
	v_pk_mul_f32 v[244:245], v[244:245], v[232:233] op_sel:[0,1] op_sel_hi:[1,1]
	v_pk_mul_f32 v[52:53], v[52:53], v[238:239]
	v_pk_mul_f32 v[54:55], v[54:55], v[240:241]
	v_pk_mul_f32 v[56:57], v[56:57], v[242:243]
	v_pk_mul_f32 v[58:59], v[58:59], v[244:245]
	v_add_u32_e32 v192, 0x90, v144
	v_ashrrev_i32_e32 v193, 31, v192
	v_lshlrev_b64 v[194:195], 12, v[192:193]
	v_lshl_add_u64 v[194:195], s[28:29], 0, v[194:195]
	v_cvt_pk_bf16_f32 v188, v56, v57
	v_cvt_pk_bf16_f32 v189, v58, v59
	v_cvt_pk_bf16_f32 v190, v52, v53
	v_cvt_pk_bf16_f32 v191, v54, v55
	v_lshl_add_u64 v[194:195], v[142:143], 1, v[194:195]
	global_store_dwordx4 v[194:195], v[188:191], off sc0 sc1
.LBB0_2048:
	s_waitcnt vmcnt(8)
	s_cmp_lg_u64 s[40:41], 0
	s_cbranch_scc1 .Lm7f_10
	v_cvt_f32_ubyte0_e32 v238, v187
	v_cvt_f32_ubyte1_e32 v239, v187
	v_cvt_f32_ubyte2_e32 v240, v187
	v_cvt_f32_ubyte3_e32 v241, v187
	v_cvt_f32_ubyte0_e32 v242, v186
	v_cvt_f32_ubyte1_e32 v243, v186
	v_cvt_f32_ubyte2_e32 v244, v186
	v_cvt_f32_ubyte3_e32 v245, v186
	v_cvt_f32_ubyte0_e32 v246, v163
	v_cvt_f32_ubyte1_e32 v247, v163
	v_cvt_f32_ubyte2_e32 v248, v163
	v_cvt_f32_ubyte3_e32 v249, v163
	v_cvt_f32_ubyte0_e32 v250, v162
	v_cvt_f32_ubyte1_e32 v251, v162
	v_cvt_f32_ubyte2_e32 v252, v162
	v_cvt_f32_ubyte3_e32 v253, v162
	v_rcp_iflag_f32_e32 v246, v246
	v_rcp_iflag_f32_e32 v247, v247
	v_rcp_iflag_f32_e32 v248, v248
	v_rcp_iflag_f32_e32 v249, v249
	v_rcp_iflag_f32_e32 v250, v250
	v_rcp_iflag_f32_e32 v251, v251
	v_rcp_iflag_f32_e32 v252, v252
	v_rcp_iflag_f32_e32 v253, v253
	v_pk_mul_f32 v[238:239], v[238:239], v[246:247]
	v_pk_mul_f32 v[240:241], v[240:241], v[248:249]
	v_pk_mul_f32 v[242:243], v[242:243], v[250:251]
	v_pk_mul_f32 v[244:245], v[244:245], v[252:253]
	v_pk_mul_f32 v[18:19], v[18:19], v[238:239]
	v_pk_mul_f32 v[20:21], v[20:21], v[240:241]
	v_pk_mul_f32 v[22:23], v[22:23], v[242:243]
	v_pk_mul_f32 v[24:25], v[24:25], v[244:245]
	s_branch .LBB0_2050
.Lm7f_10:
	s_nop 1
	v_cvt_f32_ubyte0_e32 v238, v187
	v_cvt_f32_ubyte1_e32 v239, v187
	v_cvt_f32_ubyte2_e32 v240, v187
	v_cvt_f32_ubyte3_e32 v241, v187
	v_cvt_f32_ubyte0_e32 v242, v186
	v_cvt_f32_ubyte1_e32 v243, v186
	v_cvt_f32_ubyte2_e32 v244, v186
	v_cvt_f32_ubyte3_e32 v245, v186
	v_pk_mul_f32 v[238:239], v[238:239], v[232:233] op_sel:[0,1] op_sel_hi:[1,1]
	v_pk_mul_f32 v[240:241], v[240:241], v[232:233] op_sel:[0,1] op_sel_hi:[1,1]
	v_pk_mul_f32 v[242:243], v[242:243], v[232:233] op_sel:[0,1] op_sel_hi:[1,1]
	v_pk_mul_f32 v[244:245], v[244:245], v[232:233] op_sel:[0,1] op_sel_hi:[1,1]
	v_pk_mul_f32 v[18:19], v[18:19], v[238:239]
	v_pk_mul_f32 v[20:21], v[20:21], v[240:241]
	v_pk_mul_f32 v[22:23], v[22:23], v[242:243]
	v_pk_mul_f32 v[24:25], v[24:25], v[244:245]
	v_lshlrev_b64 v[162:163], 12, v[192:193]
	v_lshl_add_u64 v[162:163], s[28:29], 0, v[162:163]
	v_cvt_pk_bf16_f32 v186, v22, v23
	v_cvt_pk_bf16_f32 v187, v24, v25
	v_cvt_pk_bf16_f32 v188, v18, v19
	v_cvt_pk_bf16_f32 v189, v20, v21
	v_lshl_add_u64 v[162:163], v[142:143], 1, v[162:163]
	global_store_dwordx4 v[162:163], v[186:189], off offset:256 sc0 sc1
.LBB0_2050:
	s_waitcnt vmcnt(6)
	s_cmp_lg_u64 s[40:41], 0
	s_cbranch_scc1 .Lm7f_11
	v_cvt_f32_ubyte0_e32 v238, v159
	v_cvt_f32_ubyte1_e32 v239, v159
	v_cvt_f32_ubyte2_e32 v240, v159
	v_cvt_f32_ubyte3_e32 v241, v159
	v_cvt_f32_ubyte0_e32 v242, v158
	v_cvt_f32_ubyte1_e32 v243, v158
	v_cvt_f32_ubyte2_e32 v244, v158
	v_cvt_f32_ubyte3_e32 v245, v158
	v_cvt_f32_ubyte0_e32 v246, v161
	v_cvt_f32_ubyte1_e32 v247, v161
	v_cvt_f32_ubyte2_e32 v248, v161
	v_cvt_f32_ubyte3_e32 v249, v161
	v_cvt_f32_ubyte0_e32 v250, v160
	v_cvt_f32_ubyte1_e32 v251, v160
	v_cvt_f32_ubyte2_e32 v252, v160
	v_cvt_f32_ubyte3_e32 v253, v160
	v_rcp_iflag_f32_e32 v246, v246
	v_rcp_iflag_f32_e32 v247, v247
	v_rcp_iflag_f32_e32 v248, v248
	v_rcp_iflag_f32_e32 v249, v249
	v_rcp_iflag_f32_e32 v250, v250
	v_rcp_iflag_f32_e32 v251, v251
	v_rcp_iflag_f32_e32 v252, v252
	v_rcp_iflag_f32_e32 v253, v253
	v_pk_mul_f32 v[238:239], v[238:239], v[246:247]
	v_pk_mul_f32 v[240:241], v[240:241], v[248:249]
	v_pk_mul_f32 v[242:243], v[242:243], v[250:251]
	v_pk_mul_f32 v[244:245], v[244:245], v[252:253]
	v_pk_mul_f32 v[44:45], v[44:45], v[238:239]
	v_pk_mul_f32 v[46:47], v[46:47], v[240:241]
	v_pk_mul_f32 v[48:49], v[48:49], v[242:243]
	v_pk_mul_f32 v[50:51], v[50:51], v[244:245]
	v_add_u32_e32 v162, 0xa0, v144
	v_ashrrev_i32_e32 v163, 31, v162
	s_branch .LBB0_2052
.Lm7f_11:
	s_nop 1
	v_cvt_f32_ubyte0_e32 v238, v159
	v_cvt_f32_ubyte1_e32 v239, v159
	v_cvt_f32_ubyte2_e32 v240, v159
	v_cvt_f32_ubyte3_e32 v241, v159
	v_cvt_f32_ubyte0_e32 v242, v158
	v_cvt_f32_ubyte1_e32 v243, v158
	v_cvt_f32_ubyte2_e32 v244, v158
	v_cvt_f32_ubyte3_e32 v245, v158
	v_pk_mul_f32 v[238:239], v[238:239], v[232:233] op_sel:[0,1] op_sel_hi:[1,1]
	v_pk_mul_f32 v[240:241], v[240:241], v[232:233] op_sel:[0,1] op_sel_hi:[1,1]
	v_pk_mul_f32 v[242:243], v[242:243], v[232:233] op_sel:[0,1] op_sel_hi:[1,1]
	v_pk_mul_f32 v[244:245], v[244:245], v[232:233] op_sel:[0,1] op_sel_hi:[1,1]
	v_pk_mul_f32 v[44:45], v[44:45], v[238:239]
	v_pk_mul_f32 v[46:47], v[46:47], v[240:241]
	v_pk_mul_f32 v[48:49], v[48:49], v[242:243]
	v_pk_mul_f32 v[50:51], v[50:51], v[244:245]
	v_add_u32_e32 v162, 0xa0, v144
	v_ashrrev_i32_e32 v163, 31, v162
	v_lshlrev_b64 v[186:187], 12, v[162:163]
	v_lshl_add_u64 v[186:187], s[28:29], 0, v[186:187]
	v_cvt_pk_bf16_f32 v158, v48, v49
	v_cvt_pk_bf16_f32 v159, v50, v51
	v_cvt_pk_bf16_f32 v160, v44, v45
	v_cvt_pk_bf16_f32 v161, v46, v47
	v_lshl_add_u64 v[186:187], v[142:143], 1, v[186:187]
	global_store_dwordx4 v[186:187], v[158:161], off sc0 sc1
; __device__ __forceinline__ unsigned cvt_pk_bf16(float lo, float hi) { f32x2c v = {lo, hi}; bf16x2c b = __builtin_convertvector(v, bf16x2c); return __builtin_bit_cast(unsigned, b); }
; __device__ __forceinline__ float ub0(unsigned w) { return (float)(w & 0xFFu); }
; __device__ __forceinline__ float ub1(unsigned w) { return (float)((w >> 8) & 0xFFu); }
; __device__ __forceinline__ float ub2(unsigned w) { return (float)((w >> 16) & 0xFFu); }
; __device__ __forceinline__ float ub3(unsigned w) { return (float)(w >> 24); }
;     __device__ __forceinline__ void operator()(f32x4 (&acc)[2][2][4][2], const Unit& u, int wr, int wc, int fr, int fq) const {
;     ...
;                 for (int bj = 0; bj < 2; ++bj) { const u32x2 a = gn[ai][m][bj], d = gd[ai][m][bj];
;                     const float an[8] = {ub0(a.x), ub1(a.x), ub2(a.x), ub3(a.x), ub0(a.y), ub1(a.y), ub2(a.y), ub3(a.y)};
;                     const float dn[8] = {ub0(d.x), ub1(d.x), ub2(d.x), ub3(d.x), ub0(d.y), ub1(d.y), ub2(d.y), ub3(d.y)};
;                     float f[8];
; #pragma unroll
;                     for (int k = 0; k < 8; ++k) { const float rd = __builtin_amdgcn_rcpf(dn[k]); f[k] = an[k] * (fin ? (1.0f / 255.0f) : rd); }
;                     f32x4 v0 = acc[ai][bj][m][0], v1 = acc[ai][bj][m][1];
;                     v0[0] *= f[0]; v0[1] *= f[1]; v0[2] *= f[2]; v0[3] *= f[3]; v1[0] *= f[4]; v1[1] *= f[5]; v1[2] *= f[6]; v1[3] *= f[7];
;                     acc[ai][bj][m][0] = v0; acc[ai][bj][m][1] = v1;
;                     if (fin) { u32x4 w; w.x = cvt_pk_bf16(v0[0], v0[1]); w.y = cvt_pk_bf16(v0[2], v0[3]); w.z = cvt_pk_bf16(v1[0], v1[1]); w.w = cvt_pk_bf16(v1[2], v1[3]);
;                         *(u32x4*)(MO + (size_t)(row0 + ai * HALF + m * 16) * ld + col0 + bj * HALF) = w; } }
.LBB0_2052:
	s_waitcnt vmcnt(4)
	s_cmp_lg_u64 s[40:41], 0
	s_cbranch_scc1 .Lm7f_12
	v_cvt_f32_ubyte0_e32 v238, v157
	v_cvt_f32_ubyte1_e32 v239, v157
	v_cvt_f32_ubyte2_e32 v240, v157
	v_cvt_f32_ubyte3_e32 v241, v157
	v_cvt_f32_ubyte0_e32 v242, v156
	v_cvt_f32_ubyte1_e32 v243, v156
	v_cvt_f32_ubyte2_e32 v244, v156
	v_cvt_f32_ubyte3_e32 v245, v156
	v_cvt_f32_ubyte0_e32 v246, v155
	v_cvt_f32_ubyte1_e32 v247, v155
	v_cvt_f32_ubyte2_e32 v248, v155
	v_cvt_f32_ubyte3_e32 v249, v155
	v_cvt_f32_ubyte0_e32 v250, v154
	v_cvt_f32_ubyte1_e32 v251, v154
	v_cvt_f32_ubyte2_e32 v252, v154
	v_cvt_f32_ubyte3_e32 v253, v154
	v_rcp_iflag_f32_e32 v246, v246
	v_rcp_iflag_f32_e32 v247, v247
	v_rcp_iflag_f32_e32 v248, v248
	v_rcp_iflag_f32_e32 v249, v249
	v_rcp_iflag_f32_e32 v250, v250
	v_rcp_iflag_f32_e32 v251, v251
	v_rcp_iflag_f32_e32 v252, v252
	v_rcp_iflag_f32_e32 v253, v253
	v_pk_mul_f32 v[238:239], v[238:239], v[246:247]
	v_pk_mul_f32 v[240:241], v[240:241], v[248:249]
	v_pk_mul_f32 v[242:243], v[242:243], v[250:251]
	v_pk_mul_f32 v[244:245], v[244:245], v[252:253]
	v_pk_mul_f32 v[10:11], v[10:11], v[238:239]
	v_pk_mul_f32 v[12:13], v[12:13], v[240:241]
	v_pk_mul_f32 v[14:15], v[14:15], v[242:243]
	v_pk_mul_f32 v[16:17], v[16:17], v[244:245]
	s_branch .LBB0_2054
.Lm7f_12:
	s_nop 1
	v_cvt_f32_ubyte0_e32 v238, v157
	v_cvt_f32_ubyte1_e32 v239, v157
	v_cvt_f32_ubyte2_e32 v240, v157
	v_cvt_f32_ubyte3_e32 v241, v157
	v_cvt_f32_ubyte0_e32 v242, v156
	v_cvt_f32_ubyte1_e32 v243, v156
	v_cvt_f32_ubyte2_e32 v244, v156
	v_cvt_f32_ubyte3_e32 v245, v156
	v_pk_mul_f32 v[238:239], v[238:239], v[232:233] op_sel:[0,1] op_sel_hi:[1,1]
	v_pk_mul_f32 v[240:241], v[240:241], v[232:233] op_sel:[0,1] op_sel_hi:[1,1]
	v_pk_mul_f32 v[242:243], v[242:243], v[232:233] op_sel:[0,1] op_sel_hi:[1,1]
	v_pk_mul_f32 v[244:245], v[244:245], v[232:233] op_sel:[0,1] op_sel_hi:[1,1]
	v_pk_mul_f32 v[10:11], v[10:11], v[238:239]
	v_pk_mul_f32 v[12:13], v[12:13], v[240:241]
	v_pk_mul_f32 v[14:15], v[14:15], v[242:243]
	v_pk_mul_f32 v[16:17], v[16:17], v[244:245]
	v_lshlrev_b64 v[158:159], 12, v[162:163]
	v_lshl_add_u64 v[158:159], s[28:29], 0, v[158:159]
	v_cvt_pk_bf16_f32 v154, v14, v15
	v_cvt_pk_bf16_f32 v155, v16, v17
	v_cvt_pk_bf16_f32 v156, v10, v11
	v_cvt_pk_bf16_f32 v157, v12, v13
	v_lshl_add_u64 v[158:159], v[142:143], 1, v[158:159]
	global_store_dwordx4 v[158:159], v[154:157], off offset:256 sc0 sc1
.LBB0_2054:
	s_waitcnt vmcnt(2)
	s_cmp_lg_u64 s[40:41], 0
	s_cbranch_scc1 .Lm7f_13
	v_cvt_f32_ubyte0_e32 v238, v151
	v_cvt_f32_ubyte1_e32 v239, v151
	v_cvt_f32_ubyte2_e32 v240, v151
	v_cvt_f32_ubyte3_e32 v241, v151
	v_cvt_f32_ubyte0_e32 v242, v150
	v_cvt_f32_ubyte1_e32 v243, v150
	v_cvt_f32_ubyte2_e32 v244, v150
	v_cvt_f32_ubyte3_e32 v245, v150
	v_cvt_f32_ubyte0_e32 v246, v153
	v_cvt_f32_ubyte1_e32 v247, v153
	v_cvt_f32_ubyte2_e32 v248, v153
	v_cvt_f32_ubyte3_e32 v249, v153
	v_cvt_f32_ubyte0_e32 v250, v152
	v_cvt_f32_ubyte1_e32 v251, v152
	v_cvt_f32_ubyte2_e32 v252, v152
	v_cvt_f32_ubyte3_e32 v253, v152
	v_rcp_iflag_f32_e32 v246, v246
	v_rcp_iflag_f32_e32 v247, v247
	v_rcp_iflag_f32_e32 v248, v248
	v_rcp_iflag_f32_e32 v249, v249
	v_rcp_iflag_f32_e32 v250, v250
	v_rcp_iflag_f32_e32 v251, v251
	v_rcp_iflag_f32_e32 v252, v252
	v_rcp_iflag_f32_e32 v253, v253
	v_pk_mul_f32 v[238:239], v[238:239], v[246:247]
	v_pk_mul_f32 v[240:241], v[240:241], v[248:249]
	v_pk_mul_f32 v[242:243], v[242:243], v[250:251]
	v_pk_mul_f32 v[244:245], v[244:245], v[252:253]
	v_pk_mul_f32 v[36:37], v[36:37], v[238:239]
	v_pk_mul_f32 v[38:39], v[38:39], v[240:241]
	v_pk_mul_f32 v[40:41], v[40:41], v[242:243]
	v_pk_mul_f32 v[42:43], v[42:43], v[244:245]
	v_add_u32_e32 v144, 0xb0, v144
	v_ashrrev_i32_e32 v145, 31, v144
	s_branch .LBB0_2056
; __device__ __forceinline__ unsigned cvt_pk_bf16(float lo, float hi) { f32x2c v = {lo, hi}; bf16x2c b = __builtin_convertvector(v, bf16x2c); return __builtin_bit_cast(unsigned, b); }
; __device__ __forceinline__ float ub0(unsigned w) { return (float)(w & 0xFFu); }
; __device__ __forceinline__ float ub1(unsigned w) { return (float)((w >> 8) & 0xFFu); }
; __device__ __forceinline__ float ub2(unsigned w) { return (float)((w >> 16) & 0xFFu); }
; __device__ __forceinline__ float ub3(unsigned w) { return (float)(w >> 24); }
;     __device__ __forceinline__ void operator()(f32x4 (&acc)[2][2][4][2], const Unit& u, int wr, int wc, int fr, int fq) const {
;     ...
;                 for (int bj = 0; bj < 2; ++bj) { const u32x2 a = gn[ai][m][bj], d = gd[ai][m][bj];
;                     const float an[8] = {ub0(a.x), ub1(a.x), ub2(a.x), ub3(a.x), ub0(a.y), ub1(a.y), ub2(a.y), ub3(a.y)};
;                     const float dn[8] = {ub0(d.x), ub1(d.x), ub2(d.x), ub3(d.x), ub0(d.y), ub1(d.y), ub2(d.y), ub3(d.y)};
;                     float f[8];
; #pragma unroll
;                     for (int k = 0; k < 8; ++k) { const float rd = __builtin_amdgcn_rcpf(dn[k]); f[k] = an[k] * (fin ? (1.0f / 255.0f) : rd); }
;                     f32x4 v0 = acc[ai][bj][m][0], v1 = acc[ai][bj][m][1];
;                     v0[0] *= f[0]; v0[1] *= f[1]; v0[2] *= f[2]; v0[3] *= f[3]; v1[0] *= f[4]; v1[1] *= f[5]; v1[2] *= f[6]; v1[3] *= f[7];
;                     acc[ai][bj][m][0] = v0; acc[ai][bj][m][1] = v1;
;                     if (fin) { u32x4 w; w.x = cvt_pk_bf16(v0[0], v0[1]); w.y = cvt_pk_bf16(v0[2], v0[3]); w.z = cvt_pk_bf16(v1[0], v1[1]); w.w = cvt_pk_bf16(v1[2], v1[3]);
;                         *(u32x4*)(MO + (size_t)(row0 + ai * HALF + m * 16) * ld + col0 + bj * HALF) = w; } }
.Lm7f_13:
	s_nop 1
	v_cvt_f32_ubyte0_e32 v238, v151
	v_cvt_f32_ubyte1_e32 v239, v151
	v_cvt_f32_ubyte2_e32 v240, v151
	v_cvt_f32_ubyte3_e32 v241, v151
	v_cvt_f32_ubyte0_e32 v242, v150
	v_cvt_f32_ubyte1_e32 v243, v150
	v_cvt_f32_ubyte2_e32 v244, v150
	v_cvt_f32_ubyte3_e32 v245, v150
	v_pk_mul_f32 v[238:239], v[238:239], v[232:233] op_sel:[0,1] op_sel_hi:[1,1]
	v_pk_mul_f32 v[240:241], v[240:241], v[232:233] op_sel:[0,1] op_sel_hi:[1,1]
	v_pk_mul_f32 v[242:243], v[242:243], v[232:233] op_sel:[0,1] op_sel_hi:[1,1]
	v_pk_mul_f32 v[244:245], v[244:245], v[232:233] op_sel:[0,1] op_sel_hi:[1,1]
	v_pk_mul_f32 v[36:37], v[36:37], v[238:239]
	v_pk_mul_f32 v[38:39], v[38:39], v[240:241]
	v_pk_mul_f32 v[40:41], v[40:41], v[242:243]
	v_pk_mul_f32 v[42:43], v[42:43], v[244:245]
	v_add_u32_e32 v144, 0xb0, v144
	v_ashrrev_i32_e32 v145, 31, v144
	v_lshlrev_b64 v[154:155], 12, v[144:145]
	v_lshl_add_u64 v[154:155], s[28:29], 0, v[154:155]
	v_cvt_pk_bf16_f32 v150, v40, v41
	v_cvt_pk_bf16_f32 v151, v42, v43
	v_cvt_pk_bf16_f32 v152, v36, v37
	v_cvt_pk_bf16_f32 v153, v38, v39
	v_lshl_add_u64 v[154:155], v[142:143], 1, v[154:155]
	global_store_dwordx4 v[154:155], v[150:153], off sc0 sc1
.LBB0_2056:
	s_waitcnt vmcnt(0)
	s_cmp_lg_u64 s[40:41], 0
	s_cbranch_scc1 .Lm7f_14
	v_cvt_f32_ubyte0_e32 v238, v149
	v_cvt_f32_ubyte1_e32 v239, v149
	v_cvt_f32_ubyte2_e32 v240, v149
	v_cvt_f32_ubyte3_e32 v241, v149
	v_cvt_f32_ubyte0_e32 v242, v148
	v_cvt_f32_ubyte1_e32 v243, v148
	v_cvt_f32_ubyte2_e32 v244, v148
	v_cvt_f32_ubyte3_e32 v245, v148
	v_cvt_f32_ubyte0_e32 v246, v147
	v_cvt_f32_ubyte1_e32 v247, v147
	v_cvt_f32_ubyte2_e32 v248, v147
	v_cvt_f32_ubyte3_e32 v249, v147
	v_cvt_f32_ubyte0_e32 v250, v146
	v_cvt_f32_ubyte1_e32 v251, v146
	v_cvt_f32_ubyte2_e32 v252, v146
	v_cvt_f32_ubyte3_e32 v253, v146
	v_rcp_iflag_f32_e32 v246, v246
	v_rcp_iflag_f32_e32 v247, v247
	v_rcp_iflag_f32_e32 v248, v248
	v_rcp_iflag_f32_e32 v249, v249
	v_rcp_iflag_f32_e32 v250, v250
	v_rcp_iflag_f32_e32 v251, v251
	v_rcp_iflag_f32_e32 v252, v252
	v_rcp_iflag_f32_e32 v253, v253
	v_pk_mul_f32 v[238:239], v[238:239], v[246:247]
	v_pk_mul_f32 v[240:241], v[240:241], v[248:249]
	v_pk_mul_f32 v[242:243], v[242:243], v[250:251]
	v_pk_mul_f32 v[244:245], v[244:245], v[252:253]
	v_pk_mul_f32 v[2:3], v[2:3], v[238:239]
	v_pk_mul_f32 v[4:5], v[4:5], v[240:241]
	v_pk_mul_f32 v[6:7], v[6:7], v[242:243]
	v_pk_mul_f32 v[8:9], v[8:9], v[244:245]
	s_branch .LBB0_2058
.Lm7f_14:
	s_nop 1
	v_cvt_f32_ubyte0_e32 v238, v149
	v_cvt_f32_ubyte1_e32 v239, v149
	v_cvt_f32_ubyte2_e32 v240, v149
	v_cvt_f32_ubyte3_e32 v241, v149
	v_cvt_f32_ubyte0_e32 v242, v148
	v_cvt_f32_ubyte1_e32 v243, v148
	v_cvt_f32_ubyte2_e32 v244, v148
	v_cvt_f32_ubyte3_e32 v245, v148
	v_pk_mul_f32 v[238:239], v[238:239], v[232:233] op_sel:[0,1] op_sel_hi:[1,1]
	v_pk_mul_f32 v[240:241], v[240:241], v[232:233] op_sel:[0,1] op_sel_hi:[1,1]
	v_pk_mul_f32 v[242:243], v[242:243], v[232:233] op_sel:[0,1] op_sel_hi:[1,1]
	v_pk_mul_f32 v[244:245], v[244:245], v[232:233] op_sel:[0,1] op_sel_hi:[1,1]
	v_pk_mul_f32 v[2:3], v[2:3], v[238:239]
	v_pk_mul_f32 v[4:5], v[4:5], v[240:241]
	v_pk_mul_f32 v[6:7], v[6:7], v[242:243]
	v_pk_mul_f32 v[8:9], v[8:9], v[244:245]
	v_lshlrev_b64 v[144:145], 12, v[144:145]
	v_lshl_add_u64 v[144:145], s[28:29], 0, v[144:145]
	v_cvt_pk_bf16_f32 v146, v6, v7
	v_cvt_pk_bf16_f32 v147, v8, v9
	v_cvt_pk_bf16_f32 v148, v2, v3
	v_cvt_pk_bf16_f32 v149, v4, v5
	v_lshl_add_u64 v[142:143], v[142:143], 1, v[144:145]
	global_store_dwordx4 v[142:143], v[146:149], off offset:256 sc0 sc1
